# baseline (speedup 1.0000x reference)
; #define PG8_STAGE(bufoff, gbase, voff) do { _Pragma("unroll") for (int _i = 0; _i < 2; ++_i) \
;         __builtin_amdgcn_global_load_lds((const unsigned*)((const char*)(gbase) + (voff)[_i]), (PG8_LAS unsigned*)(lds + (bufoff) + ldsw + _i * 8192), 16, 0, 0); } while (0)
; #define PG8_WAIT_V(n) asm volatile("s_waitcnt vmcnt(" #n ")" ::: "memory")
; #define PG8_BAR __builtin_amdgcn_s_barrier()
; template <class Epi, class Sched, bool ALIGN_EPI = false, bool SP2 = false>
; __device__ __forceinline__ void gemm_phase(PG8_LAS unsigned char* lds, const Gemm g, const Sched& S, const Epi& E) {
;     ...
;     const char* cA = (const char*)g.A + (size_t)cur.pm * tstep + (size_t)cur.kt0 * kstep; const char* cB = (const char*)g.Bt + (size_t)cur.pn * tstep + (size_t)cur.kt0 * kstep;
;     S.a_ready(cur);
;     if constexpr (SP2) {
;         PG8_STAGE(PG8_SB(0, 0), cB, voffB); PG8_STAGE(PG8_SB(0, 1), cB + hstep, voffB); PG8_STAGE(PG8_SA(0, 0), cA, voffA); PG8_STAGE(PG8_SA(0, 1), cA + hstep, voffA);
;         if (wr == 1) PG8_BAR;
;         PG8_WAIT_V(2); PG8_BAR;
;         PG8_STAGE(PG8_SB(1, 0), cB + kstep, voffB); PG8_STAGE(PG8_SA(1, 0), cA + kstep, voffA); PG8_STAGE(PG8_SB(1, 1), cB + hstep + kstep, voffB);
;         PG8_WAIT_V(6); PG8_BAR;
;     ...
;         const bool has_next = S.next(ui + 1, nxt);
;         const long nks = has_next ? (((ui + 1) & 1) ? -kstep : kstep) : ks;
;         const long nk0 = (long)(nxt.kt0 + (nks < 0 ? nxt.nkt - 1 : 0)) * kstep;
;         const char* nA = has_next ? (const char*)g.A + (size_t)nxt.pm * tstep + nk0 : cA; const char* nB = has_next ? (const char*)g.Bt + (size_t)nxt.pn * tstep + nk0 : cB;
.LBB0_343:
	s_lshl_b32 s4, s19, 5
	s_xor_b64 s[26:27], s[26:27], -1
	s_lshl_b32 s33, s18, 13
	s_and_b32 s19, s4, 0x60
	s_add_u32 s70, s58, 0x1b800000
	s_mov_b64 s[44:45], 0x80
	s_addc_u32 s71, s59, 0
	s_add_i32 m0, s98, 0x18000
	v_lshl_add_u64 v[10:11], v[10:11], 0, s[44:45]
	s_waitcnt vmcnt(2)
	s_barrier
	global_load_lds_dwordx4 v[10:11], off
	v_lshl_add_u64 v[6:7], v[6:7], 0, s[44:45]
	s_add_i32 m0, s98, 0x1a000
	s_add_i32 s72, s98, 0x8000
	global_load_lds_dwordx4 v[6:7], off
	v_lshl_add_u64 v[6:7], v[8:9], 0, s[44:45]
	s_mov_b32 m0, s72
	s_add_i32 s73, s98, 0xa000
	global_load_lds_dwordx4 v[6:7], off
	v_lshl_add_u64 v[6:7], v[12:13], 0, s[44:45]
	s_mov_b32 m0, s73
	v_lshl_add_u64 v[4:5], v[4:5], 0, s[44:45]
	global_load_lds_dwordx4 v[6:7], off
	s_add_i32 m0, s98, 0x1c000
	v_lshl_add_u64 v[2:3], v[2:3], 0, s[44:45]
	global_load_lds_dwordx4 v[4:5], off
	s_add_i32 m0, s98, 0x1e000
	s_cmpk_lt_u32 s5, 0x100
	global_load_lds_dwordx4 v[2:3], off
	v_mul_f32_e32 v3, v16, v17
	v_trunc_f32_e32 v3, v3
	v_cvt_u32_f32_e32 v4, v3
	v_fma_f32 v3, -v3, v15, v16
	s_cselect_b64 s[28:29], -1, 0
	s_lshr_b32 s91, s79, s12
	s_lshr_b32 s75, s52, 3
	v_cmp_ge_f32_e64 s[4:5], |v3|, v15
	v_readfirstlane_b32 s12, v4
	s_cmp_lg_u64 s[4:5], 0
	s_addc_u32 s4, s12, 0
	s_and_b32 s76, s4, 0x7ff
	v_cvt_f32_u32_e32 v3, s76
	v_lshlrev_b32_e32 v4, 2, v197
	v_lshl_or_b32 v2, v197, 6, v198
	v_and_b32_e32 v4, 32, v4
	v_bitop3_b32 v4, v2, s33, v4 bitop3:0xde
	v_rcp_iflag_f32_e32 v2, v3
	v_rcp_iflag_f32_e32 v3, v18
	s_sub_i32 s4, 0, s76
	s_waitcnt vmcnt(0)
	v_mul_f32_e32 v2, 0x4f7ffffe, v2
	v_cvt_u32_f32_e32 v2, v2
	v_lshl_or_b32 v144, s18, 6, v197
	v_lshl_or_b32 v145, s19, 7, v199
	v_add_u32_e32 v242, 0x10000, v145
	v_or_b32_e32 v146, s19, v192
	v_readfirstlane_b32 s5, v2
	v_mul_f32_e32 v2, 0x4f7ffffe, v14
	v_cvt_u32_f32_e32 v2, v2
	s_mul_i32 s4, s4, s5
	s_mul_hi_u32 s4, s5, s4
	s_add_i32 s77, s5, s4
	v_readfirstlane_b32 s5, v2
	v_mul_f32_e32 v2, 0x4f7ffffe, v3
	v_cvt_u32_f32_e32 v2, v2
	s_sub_i32 s4, 0, s7
	s_mul_i32 s4, s4, s5
	s_mul_hi_u32 s4, s5, s4
	s_add_i32 s69, s5, s4
	s_sub_i32 s4, 0, s78
	v_readfirstlane_b32 s5, v2
	s_mul_i32 s4, s4, s5
	v_add_lshl_u32 v2, v200, v19, 1
	v_mov_b32_e32 v3, v1
	s_mul_hi_u32 s4, s5, s4
	v_lshl_add_u64 v[136:137], s[16:17], 0, v[2:3]
	v_add_lshl_u32 v2, v200, v20, 1
	s_mov_b32 s18, 0
	s_add_i32 s5, s5, s4
	v_lshl_add_u64 v[138:139], s[16:17], 0, v[2:3]
	v_add_u32_e32 v147, 0, v4
	s_barrier
	s_branch .LBB0_346

; #define PG8_STAGE(bufoff, gbase, voff) do { _Pragma("unroll") for (int _i = 0; _i < 2; ++_i) \
;         __builtin_amdgcn_global_load_lds((const unsigned*)((const char*)(gbase) + (voff)[_i]), (PG8_LAS unsigned*)(lds + (bufoff) + ldsw + _i * 8192), 16, 0, 0); } while (0)
; #define PG8_LDA(dst, b, h) do { _Pragma("unroll") for (int m = 0; m < 4; ++m) _Pragma("unroll") for (int k = 0; k < 2; ++k) dst[m][k] = *(const PG8_LAS bf16x8*)(lds + PG8_SA(b, h) + aoff + m * 2048 + k * 1024); } while (0)
; #define PG8_LDB(dst, b, h) do { _Pragma("unroll") for (int n = 0; n < 2; ++n) _Pragma("unroll") for (int k = 0; k < 2; ++k) dst[n][k] = *(const PG8_LAS bf16x8*)(lds + PG8_SB(b, h) + boff + n * 2048 + k * 1024); } while (0)
; #define PG8_MMA(ai, bj, At, Bt) do { __builtin_amdgcn_s_setprio(1); _Pragma("unroll") for (int m = 0; m < 4; ++m) _Pragma("unroll") for (int n = 0; n < 2; ++n) _Pragma("unroll") for (int k = 0; k < 2; ++k) \
;         acc[ai][bj][m][n] = __builtin_amdgcn_mfma_f32_16x16x32_bf16(Bt[n][k], At[m][k], acc[ai][bj][m][n], 0, 0, 0); __builtin_amdgcn_s_setprio(0); } while (0)
; #define PG8_WAIT_V(n) asm volatile("s_waitcnt vmcnt(" #n ")" ::: "memory")
; #define PG8_WAIT_L(n) asm volatile("s_waitcnt lgkmcnt(" #n ")" ::: "memory")
; #define PG8_BAR __builtin_amdgcn_s_barrier()
; #define PG8_SCHED __builtin_amdgcn_sched_barrier(0)
; template <class Epi, class Sched, bool ALIGN_EPI = false, bool SP2 = false>
; __device__ __forceinline__ void gemm_phase(PG8_LAS unsigned char* lds, const Gemm g, const Sched& S, const Epi& E) {
;     ...
;             if constexpr (SP2) {
;             PG8_LDB(B0, 0, 0); PG8_LDB(B1, 0, 1); PG8_SCHED; PG8_LDA(At, 0, 0); PG8_STAGE(PG8_SA(1, 1), a1 + hstep, voffA);
;             PG8_WAIT_V(8); PG8_WAIT_L(0); PG8_BAR; PG8_MMA(0, 0, At, B0); PG8_MMA(0, 1, At, B1); PG8_BAR; PG8_SCHED;
;             PG8_LDA(At, 0, 1); PG8_STAGE(PG8_SB(0, 0), b2, voffB); PG8_STAGE(PG8_SB(0, 1), b2 + hstep, voffB); PG8_STAGE(PG8_SA(0, 0), a2, voffA);
;             PG8_WAIT_V(8); PG8_WAIT_L(0); PG8_BAR; PG8_MMA(1, 0, At, B0); PG8_MMA(1, 1, At, B1); PG8_BAR; PG8_SCHED;
.LBB0_355:
	s_add_i32 s80, s80, 2
	s_add_u32 s82, s62, s60
	s_addc_u32 s83, s63, s61
	v_lshl_add_u64 v[232:233], v[140:141], 0, s[50:51]
	s_add_i32 m0, s98, 0xc000
	global_load_lds_dwordx4 v[232:233], off
	v_lshl_add_u64 v[232:233], v[142:143], 0, s[50:51]
	s_add_i32 m0, s98, 0xe000
	s_nop 0
	global_load_lds_dwordx4 v[232:233], off
	s_setprio 1
	s_waitcnt vmcnt(18) lgkmcnt(0)
	s_barrier
	v_mfma_f32_16x16x32_bf16 v[126:129], v[148:151], v[182:185], 0
	v_mfma_f32_16x16x32_bf16 v[122:125], v[156:159], v[182:185], 0
	v_mfma_f32_16x16x32_bf16 v[118:121], v[148:151], v[208:211], 0
	v_mfma_f32_16x16x32_bf16 v[110:113], v[156:159], v[208:211], 0
	v_mfma_f32_16x16x32_bf16 v[102:105], v[148:151], v[216:219], 0
	v_mfma_f32_16x16x32_bf16 v[94:97], v[156:159], v[216:219], 0
	v_mfma_f32_16x16x32_bf16 v[86:89], v[148:151], v[224:227], 0
	v_mfma_f32_16x16x32_bf16 v[78:81], v[156:159], v[224:227], 0
	v_mfma_f32_16x16x32_bf16 v[126:129], v[152:155], v[186:189], v[126:129]
	v_mfma_f32_16x16x32_bf16 v[122:125], v[160:163], v[186:189], v[122:125]
	v_mfma_f32_16x16x32_bf16 v[118:121], v[152:155], v[212:215], v[118:121]
	v_mfma_f32_16x16x32_bf16 v[110:113], v[160:163], v[212:215], v[110:113]
	v_mfma_f32_16x16x32_bf16 v[102:105], v[152:155], v[220:223], v[102:105]
	v_mfma_f32_16x16x32_bf16 v[94:97], v[160:163], v[220:223], v[94:97]
	v_mfma_f32_16x16x32_bf16 v[86:89], v[152:155], v[228:231], v[86:89]
	v_mfma_f32_16x16x32_bf16 v[78:81], v[160:163], v[228:231], v[78:81]
	v_mfma_f32_16x16x32_bf16 v[114:117], v[164:167], v[182:185], 0
	v_mfma_f32_16x16x32_bf16 v[106:109], v[172:175], v[182:185], 0
	v_mfma_f32_16x16x32_bf16 v[98:101], v[164:167], v[208:211], 0
	v_mfma_f32_16x16x32_bf16 v[90:93], v[172:175], v[208:211], 0
	v_mfma_f32_16x16x32_bf16 v[82:85], v[164:167], v[216:219], 0
	v_mfma_f32_16x16x32_bf16 v[74:77], v[172:175], v[216:219], 0
	v_mfma_f32_16x16x32_bf16 v[70:73], v[164:167], v[224:227], 0
	v_mfma_f32_16x16x32_bf16 v[66:69], v[172:175], v[224:227], 0
	v_mfma_f32_16x16x32_bf16 v[114:117], v[168:171], v[186:189], v[114:117]
	v_mfma_f32_16x16x32_bf16 v[106:109], v[176:179], v[186:189], v[106:109]
	v_mfma_f32_16x16x32_bf16 v[98:101], v[168:171], v[212:215], v[98:101]
	v_mfma_f32_16x16x32_bf16 v[90:93], v[176:179], v[212:215], v[90:93]
	v_mfma_f32_16x16x32_bf16 v[82:85], v[168:171], v[220:223], v[82:85]
	v_mfma_f32_16x16x32_bf16 v[74:77], v[176:179], v[220:223], v[74:77]
	v_mfma_f32_16x16x32_bf16 v[70:73], v[168:171], v[228:231], v[70:73]
	v_mfma_f32_16x16x32_bf16 v[66:69], v[176:179], v[228:231], v[66:69]
	s_setprio 0
	s_barrier
	s_add_i32 m0, s97, 0x10000
	ds_read_b128 v[182:185], v147 offset:16384
	ds_read_b128 v[186:189], v147 offset:17408
	ds_read_b128 v[208:211], v147 offset:18432
	ds_read_b128 v[212:215], v147 offset:19456
	ds_read_b128 v[216:219], v147 offset:20480
	ds_read_b128 v[220:223], v147 offset:21504
	ds_read_b128 v[224:227], v147 offset:22528
	ds_read_b128 v[228:231], v147 offset:23552
	global_load_lds_dwordx4 v0, s[56:57]
	s_add_i32 m0, s97, 0x12000
	s_add_u32 s38, s56, s16
	s_addc_u32 s39, s57, 0
	global_load_lds_dwordx4 v134, s[56:57]
	s_add_i32 m0, s97, 0x14000
	s_nop 0
	global_load_lds_dwordx4 v0, s[38:39]
	s_add_i32 m0, s97, 0x16000
	s_nop 0
	global_load_lds_dwordx4 v134, s[38:39]
	s_mov_b32 m0, s98
	s_nop 0
	global_load_lds_dwordx4 v130, s[62:63]
	s_mov_b32 m0, s99
	s_nop 0
	global_load_lds_dwordx4 v132, s[62:63]
	s_setprio 1
	s_waitcnt vmcnt(24) lgkmcnt(0)
	s_barrier
	v_mfma_f32_16x16x32_bf16 v[62:65], v[148:151], v[182:185], 0
	v_mfma_f32_16x16x32_bf16 v[58:61], v[156:159], v[182:185], 0
	v_mfma_f32_16x16x32_bf16 v[54:57], v[148:151], v[208:211], 0
	v_mfma_f32_16x16x32_bf16 v[46:49], v[156:159], v[208:211], 0
	v_mfma_f32_16x16x32_bf16 v[38:41], v[148:151], v[216:219], 0
	v_mfma_f32_16x16x32_bf16 v[30:33], v[156:159], v[216:219], 0
	v_mfma_f32_16x16x32_bf16 v[22:25], v[148:151], v[224:227], 0
	v_mfma_f32_16x16x32_bf16 v[14:17], v[156:159], v[224:227], 0
	v_mfma_f32_16x16x32_bf16 v[62:65], v[152:155], v[186:189], v[62:65]
	v_mfma_f32_16x16x32_bf16 v[58:61], v[160:163], v[186:189], v[58:61]
	v_mfma_f32_16x16x32_bf16 v[54:57], v[152:155], v[212:215], v[54:57]
	v_mfma_f32_16x16x32_bf16 v[46:49], v[160:163], v[212:215], v[46:49]
	v_mfma_f32_16x16x32_bf16 v[38:41], v[152:155], v[220:223], v[38:41]
	v_mfma_f32_16x16x32_bf16 v[30:33], v[160:163], v[220:223], v[30:33]
	v_mfma_f32_16x16x32_bf16 v[22:25], v[152:155], v[228:231], v[22:25]
	v_mfma_f32_16x16x32_bf16 v[14:17], v[160:163], v[228:231], v[14:17]
	v_mfma_f32_16x16x32_bf16 v[50:53], v[164:167], v[182:185], 0
	v_mfma_f32_16x16x32_bf16 v[42:45], v[172:175], v[182:185], 0
	v_mfma_f32_16x16x32_bf16 v[34:37], v[164:167], v[208:211], 0
	v_mfma_f32_16x16x32_bf16 v[26:29], v[172:175], v[208:211], 0
	v_mfma_f32_16x16x32_bf16 v[18:21], v[164:167], v[216:219], 0
	v_mfma_f32_16x16x32_bf16 v[10:13], v[172:175], v[216:219], 0
	v_mfma_f32_16x16x32_bf16 v[6:9], v[164:167], v[224:227], 0
	v_mfma_f32_16x16x32_bf16 v[2:5], v[172:175], v[224:227], 0
	v_mfma_f32_16x16x32_bf16 v[50:53], v[168:171], v[186:189], v[50:53]
	v_mfma_f32_16x16x32_bf16 v[42:45], v[176:179], v[186:189], v[42:45]
	v_mfma_f32_16x16x32_bf16 v[34:37], v[168:171], v[212:215], v[34:37]
	v_mfma_f32_16x16x32_bf16 v[26:29], v[176:179], v[212:215], v[26:29]
	v_mfma_f32_16x16x32_bf16 v[18:21], v[168:171], v[220:223], v[18:21]
	v_mfma_f32_16x16x32_bf16 v[10:13], v[176:179], v[220:223], v[10:13]
	v_mfma_f32_16x16x32_bf16 v[6:9], v[168:171], v[228:231], v[6:9]
	v_mfma_f32_16x16x32_bf16 v[2:5], v[176:179], v[228:231], v[2:5]
	s_setprio 0
	s_barrier
; #define PG8_STAGE(bufoff, gbase, voff) do { _Pragma("unroll") for (int _i = 0; _i < 2; ++_i) \
;         __builtin_amdgcn_global_load_lds((const unsigned*)((const char*)(gbase) + (voff)[_i]), (PG8_LAS unsigned*)(lds + (bufoff) + ldsw + _i * 8192), 16, 0, 0); } while (0)
; #define PG8_LDA(dst, b, h) do { _Pragma("unroll") for (int m = 0; m < 4; ++m) _Pragma("unroll") for (int k = 0; k < 2; ++k) dst[m][k] = *(const PG8_LAS bf16x8*)(lds + PG8_SA(b, h) + aoff + m * 2048 + k * 1024); } while (0)
; #define PG8_LDB(dst, b, h) do { _Pragma("unroll") for (int n = 0; n < 2; ++n) _Pragma("unroll") for (int k = 0; k < 2; ++k) dst[n][k] = *(const PG8_LAS bf16x8*)(lds + PG8_SB(b, h) + boff + n * 2048 + k * 1024); } while (0)
; #define PG8_MMA(ai, bj, At, Bt) do { __builtin_amdgcn_s_setprio(1); _Pragma("unroll") for (int m = 0; m < 4; ++m) _Pragma("unroll") for (int n = 0; n < 2; ++n) _Pragma("unroll") for (int k = 0; k < 2; ++k) \
;         acc[ai][bj][m][n] = __builtin_amdgcn_mfma_f32_16x16x32_bf16(Bt[n][k], At[m][k], acc[ai][bj][m][n], 0, 0, 0); __builtin_amdgcn_s_setprio(0); } while (0)
; #define PG8_WAIT_V(n) asm volatile("s_waitcnt vmcnt(" #n ")" ::: "memory")
; #define PG8_WAIT_L(n) asm volatile("s_waitcnt lgkmcnt(" #n ")" ::: "memory")
; template <class Epi, class Sched, bool ALIGN_EPI = false, bool SP2 = false>
; __device__ __forceinline__ void gemm_phase(PG8_LAS unsigned char* lds, const Gemm g, const Sched& S, const Epi& E) {
;     ...
;         for (int t = 0; t < nt; t += 2) {
;             const bool last = (t == nt - 2);
;             const char* a1 = cA + (long)(t + 1) * ks;
;             const char* a2 = last ? nA : cA + (long)(t + 2) * ks; const char* b2 = last ? nB : cB + (long)(t + 2) * ks;
;             const long ks3 = last ? nks : ks; const char* a3 = a2 + ks3; const char* b3 = b2 + ks3;
;             if (last && has_next) S.a_ready(nxt);
;     ...
;             PG8_LDB(B0, 1, 0); PG8_LDB(B1, 1, 1); PG8_SCHED; PG8_LDA(At, 1, 0); PG8_STAGE(PG8_SA(0, 1), a2 + hstep, voffA);
;             PG8_WAIT_V(8); PG8_WAIT_L(0); PG8_BAR; PG8_MMA(0, 0, At, B0); PG8_MMA(0, 1, At, B1); PG8_BAR; PG8_SCHED;
;             PG8_LDA(At, 1, 1); PG8_STAGE(PG8_SB(1, 0), b3, voffB); PG8_STAGE(PG8_SB(1, 1), b3 + hstep, voffB); PG8_STAGE(PG8_SA(1, 0), a3, voffA);
;             PG8_WAIT_V(8); PG8_WAIT_L(0); PG8_BAR; PG8_MMA(1, 0, At, B0); PG8_MMA(1, 1, At, B1); PG8_BAR; PG8_SCHED;
	ds_read_b128 v[148:151], v242 offset:32768
	ds_read_b128 v[152:155], v242 offset:33792
	ds_read_b128 v[156:159], v242 offset:34816
	ds_read_b128 v[160:163], v242 offset:35840
	ds_read_b128 v[164:167], v242 offset:49152
	ds_read_b128 v[168:171], v242 offset:50176
	ds_read_b128 v[172:175], v242 offset:51200
	ds_read_b128 v[176:179], v242 offset:52224
	s_add_u32 s38, s62, s16
	s_addc_u32 s39, s63, 0
	s_mov_b32 m0, s68
	ds_read_b128 v[182:185], v147 offset:32768
	ds_read_b128 v[186:189], v147 offset:33792
	ds_read_b128 v[208:211], v147 offset:34816
	ds_read_b128 v[212:215], v147 offset:35840
	ds_read_b128 v[216:219], v147 offset:36864
	ds_read_b128 v[220:223], v147 offset:37888
	ds_read_b128 v[224:227], v147 offset:38912
	ds_read_b128 v[228:231], v147 offset:39936
	global_load_lds_dwordx4 v130, s[38:39]
	s_mov_b32 m0, s64
	s_nop 0
	global_load_lds_dwordx4 v132, s[38:39]
	s_setprio 1
	s_waitcnt vmcnt(8) lgkmcnt(0)
	s_barrier
	v_mfma_f32_16x16x32_bf16 v[126:129], v[148:151], v[182:185], v[126:129]
	v_mfma_f32_16x16x32_bf16 v[122:125], v[156:159], v[182:185], v[122:125]
	v_mfma_f32_16x16x32_bf16 v[118:121], v[148:151], v[208:211], v[118:121]
	v_mfma_f32_16x16x32_bf16 v[110:113], v[156:159], v[208:211], v[110:113]
	v_mfma_f32_16x16x32_bf16 v[102:105], v[148:151], v[216:219], v[102:105]
	v_mfma_f32_16x16x32_bf16 v[94:97], v[156:159], v[216:219], v[94:97]
	v_mfma_f32_16x16x32_bf16 v[86:89], v[148:151], v[224:227], v[86:89]
	v_mfma_f32_16x16x32_bf16 v[78:81], v[156:159], v[224:227], v[78:81]
	v_mfma_f32_16x16x32_bf16 v[126:129], v[152:155], v[186:189], v[126:129]
	v_mfma_f32_16x16x32_bf16 v[122:125], v[160:163], v[186:189], v[122:125]
	v_mfma_f32_16x16x32_bf16 v[118:121], v[152:155], v[212:215], v[118:121]
	v_mfma_f32_16x16x32_bf16 v[110:113], v[160:163], v[212:215], v[110:113]
	v_mfma_f32_16x16x32_bf16 v[102:105], v[152:155], v[220:223], v[102:105]
	v_mfma_f32_16x16x32_bf16 v[94:97], v[160:163], v[220:223], v[94:97]
	v_mfma_f32_16x16x32_bf16 v[86:89], v[152:155], v[228:231], v[86:89]
	v_mfma_f32_16x16x32_bf16 v[78:81], v[160:163], v[228:231], v[78:81]
	v_mfma_f32_16x16x32_bf16 v[114:117], v[164:167], v[182:185], v[114:117]
	v_mfma_f32_16x16x32_bf16 v[106:109], v[172:175], v[182:185], v[106:109]
	v_mfma_f32_16x16x32_bf16 v[98:101], v[164:167], v[208:211], v[98:101]
	v_mfma_f32_16x16x32_bf16 v[90:93], v[172:175], v[208:211], v[90:93]
	v_mfma_f32_16x16x32_bf16 v[82:85], v[164:167], v[216:219], v[82:85]
	v_mfma_f32_16x16x32_bf16 v[74:77], v[172:175], v[216:219], v[74:77]
	v_mfma_f32_16x16x32_bf16 v[70:73], v[164:167], v[224:227], v[70:73]
	v_mfma_f32_16x16x32_bf16 v[66:69], v[172:175], v[224:227], v[66:69]
	v_mfma_f32_16x16x32_bf16 v[114:117], v[168:171], v[186:189], v[114:117]
	v_mfma_f32_16x16x32_bf16 v[106:109], v[176:179], v[186:189], v[106:109]
	v_mfma_f32_16x16x32_bf16 v[98:101], v[168:171], v[212:215], v[98:101]
	v_mfma_f32_16x16x32_bf16 v[90:93], v[176:179], v[212:215], v[90:93]
	v_mfma_f32_16x16x32_bf16 v[82:85], v[168:171], v[220:223], v[82:85]
	v_mfma_f32_16x16x32_bf16 v[74:77], v[176:179], v[220:223], v[74:77]
	v_mfma_f32_16x16x32_bf16 v[70:73], v[168:171], v[228:231], v[70:73]
	v_mfma_f32_16x16x32_bf16 v[66:69], v[176:179], v[228:231], v[66:69]
	s_setprio 0
	s_barrier
	s_add_u32 s38, s56, s60
	s_addc_u32 s39, s57, s61
	s_add_i32 m0, s97, 0x18000
	ds_read_b128 v[182:185], v147 offset:49152
	ds_read_b128 v[186:189], v147 offset:50176
	ds_read_b128 v[208:211], v147 offset:51200
	ds_read_b128 v[212:215], v147 offset:52224
	ds_read_b128 v[216:219], v147 offset:53248
	ds_read_b128 v[220:223], v147 offset:54272
	ds_read_b128 v[224:227], v147 offset:55296
	ds_read_b128 v[228:231], v147 offset:56320
	global_load_lds_dwordx4 v0, s[38:39]
	s_add_i32 m0, s97, 0x1a000
	s_nop 0
	global_load_lds_dwordx4 v134, s[38:39]
	s_add_u32 s38, s38, s16
	s_addc_u32 s39, s39, 0
	s_add_i32 m0, s97, 0x1c000
	global_load_lds_dwordx4 v0, s[38:39]
	s_add_i32 m0, s97, 0x1e000
	s_nop 0
	global_load_lds_dwordx4 v134, s[38:39]
	s_mov_b32 m0, s72
	s_nop 0
	global_load_lds_dwordx4 v130, s[82:83]
	s_mov_b32 m0, s73
	s_nop 0
	global_load_lds_dwordx4 v132, s[82:83]
	s_add_u32 s50, s50, s48
	s_addc_u32 s51, s51, s49
	s_cmp_ge_u32 s80, s13
	s_cselect_b64 vcc, -1, 0
	s_cbranch_scc1 .Lgemm_ctl_done_p
	s_cmp_eq_u32 s88, s80
	s_cbranch_scc1 .Lgemm_ctl_last_p
	s_add_u32 s62, s18, s50
	s_addc_u32 s63, s19, s51
	s_add_u32 s56, s87, s50
	s_addc_u32 s57, s33, s51
	s_mov_b64 s[60:61], s[44:45]
	s_branch .Lgemm_ctl_join_p

; __device__ __forceinline__ unsigned cvt_pk_bf16(float lo, float hi) { unsigned r; asm volatile("v_cvt_pk_bf16_f32 %0, %1, %2" : "=v"(r) : "v"(lo), "v"(hi)); return r; }
;     __device__ __forceinline__ void operator()(const f32x4 (&acc)[2][2][4][2], const Unit& u, int wr, int wc, int fr, int fq) const {
;     ...
;         const int col0 = u.pn * HALF + wc * 32 + 8 * fq;
; #pragma unroll
;         for (int ai = 0; ai < 2; ++ai)
; #pragma unroll
;             for (int m = 0; m < 4; ++m) { bf16_t* rowp = O + (size_t)(row0 + ai * HALF + m * 16) * ldc + col0;
;                 f32x2 h[4];
; #pragma unroll
;                 for (int n = 0; n < 2; ++n)
; #pragma unroll
;                     for (int j = 0; j < 2; ++j) { const f32x2 g = {acc[ai][0][m][n][2 * j], acc[ai][0][m][n][2 * j + 1]}, up = {acc[ai][1][m][n][2 * j], acc[ai][1][m][n][2 * j + 1]};
;                         const f32x2 t = g * (-1.44269504089f); f32x2 e; e.x = __builtin_amdgcn_exp2f(t.x); e.y = __builtin_amdgcn_exp2f(t.y);
;                         const f32x2 d = e + 1.0f; f32x2 r; r.x = __builtin_amdgcn_rcpf(d.x); r.y = __builtin_amdgcn_rcpf(d.y);
;                         h[n * 2 + j] = (g * r) * up; }
;                 u32x4 w; w.x = cvt_pk_bf16(h[0].x, h[0].y); w.y = cvt_pk_bf16(h[1].x, h[1].y); w.z = cvt_pk_bf16(h[2].x, h[2].y); w.w = cvt_pk_bf16(h[3].x, h[3].y);
;                 *(u32x4*)rowp = w; }
.LBB0_362:
	s_waitcnt vmcnt(0)
	v_lshrrev_b32_e32 v254, 2, v206
	v_and_b32_e32 v255, 15, v206
	v_sub_u32_e32 v252, v254, v255
	v_mul_lo_u32 v252, v252, s20
	v_lshlrev_b32_e32 v252, 1, v252
	v_and_b32_e32 v253, 3, v206
	v_lshrrev_b32_e32 v255, 4, v206
	v_sub_u32_e32 v253, v253, v255
	v_lshl_add_u32 v252, v253, 4, v252
	v_ashrrev_i32_e32 v253, 31, v252
	v_lshrrev_b32_e32 v255, 6, v180
	v_mul_u32_u24_e32 v255, 0x500, v255
	v_add_u32_e32 v255, 0x20000, v255
	v_and_b32_e32 v244, 15, v206
	v_mul_u32_u24_e32 v244, 0x50, v244
	v_lshrrev_b32_e32 v245, 4, v206
	v_lshl_add_u32 v244, v245, 4, v244
	v_add_u32_e32 v244, v244, v255
	v_mul_u32_u24_e32 v245, 0x50, v254
	v_and_b32_e32 v254, 3, v206
	v_lshl_add_u32 v245, v254, 4, v245
	v_add_u32_e32 v245, v245, v255
	v_lshl_add_u32 v148, s31, 8, v144
	s_cmp_lt_i32 s30, 0
	s_mov_b64 s[38:39], -1
	s_mov_b32 s60, 0x14000
	s_cbranch_scc0 .LBB0_369
	v_mad_i64_i32 v[140:141], s[18:19], s20, v148, 0
	v_lshl_add_u64 v[140:141], v[140:141], 1, s[8:9]
	s_and_b64 vcc, exec, s[26:27]
	v_or_b32_e32 v155, 16, v148
	v_or_b32_e32 v154, 32, v148
	v_or_b32_e32 v153, 48, v148
	v_add_u32_e32 v152, 0x80, v148
	v_add_u32_e32 v151, 0x90, v148
	v_add_u32_e32 v150, 0xa0, v148
	v_add_u32_e32 v149, 0xb0, v148
	s_cbranch_vccz .LBB0_365
	v_pk_mul_f32 v[156:157], v[126:127], s[92:93] op_sel_hi:[1,0]
	v_pk_mul_f32 v[158:159], v[128:129], s[92:93] op_sel_hi:[1,0]
	v_exp_f32_e32 v156, v156
	v_exp_f32_e32 v157, v157
	v_exp_f32_e32 v158, v158
	v_exp_f32_e32 v159, v159
	v_pk_mul_f32 v[160:161], v[122:123], s[92:93] op_sel_hi:[1,0]
	v_pk_mul_f32 v[162:163], v[124:125], s[92:93] op_sel_hi:[1,0]
	v_exp_f32_e32 v160, v160
	v_exp_f32_e32 v161, v161
	v_exp_f32_e32 v162, v162
	v_exp_f32_e32 v163, v163
	v_pk_add_f32 v[156:157], v[156:157], 1.0 op_sel_hi:[1,0]
	v_pk_add_f32 v[158:159], v[158:159], 1.0 op_sel_hi:[1,0]
	v_rcp_f32_e32 v156, v156
	v_rcp_f32_e32 v157, v157
	v_rcp_f32_e32 v158, v158
	v_rcp_f32_e32 v159, v159
	v_pk_add_f32 v[160:161], v[160:161], 1.0 op_sel_hi:[1,0]
	v_pk_add_f32 v[162:163], v[162:163], 1.0 op_sel_hi:[1,0]
	v_rcp_f32_e32 v160, v160
	v_rcp_f32_e32 v161, v161
	v_rcp_f32_e32 v162, v162
	v_rcp_f32_e32 v163, v163
	v_lshl_or_b32 v142, s67, 7, v146
	v_ashrrev_i32_e32 v143, 31, v142
	v_pk_mul_f32 v[156:157], v[126:127], v[156:157]
	v_pk_mul_f32 v[158:159], v[128:129], v[158:159]
	v_pk_mul_f32 v[156:157], v[114:115], v[156:157]
	v_pk_mul_f32 v[158:159], v[116:117], v[158:159]
	v_pk_mul_f32 v[160:161], v[122:123], v[160:161]
	v_pk_mul_f32 v[162:163], v[124:125], v[162:163]
	v_lshlrev_b64 v[142:143], 1, v[142:143]
	v_pk_mul_f32 v[160:161], v[106:107], v[160:161]
	v_pk_mul_f32 v[162:163], v[108:109], v[162:163]
	v_lshl_add_u64 v[164:165], v[140:141], 0, v[142:143]
	v_cvt_pk_bf16_f32 v156, v156, v157
	v_cvt_pk_bf16_f32 v157, v158, v159
	v_cvt_pk_bf16_f32 v158, v160, v161
	v_cvt_pk_bf16_f32 v159, v162, v163
	ds_write_b128 v244, v[156:159]
	v_lshl_add_u64 v[246:247], v[164:165], 0, v[252:253]
	ds_read_b128 v[248:251], v245
	v_pk_mul_f32 v[160:161], v[120:121], s[92:93] op_sel_hi:[1,0]
	v_pk_mul_f32 v[162:163], v[110:111], s[92:93] op_sel_hi:[1,0]
	v_pk_mul_f32 v[158:159], v[118:119], s[92:93] op_sel_hi:[1,0]
	v_pk_mul_f32 v[164:165], v[112:113], s[92:93] op_sel_hi:[1,0]
	v_exp_f32_e32 v158, v158
	v_exp_f32_e32 v159, v159
	v_exp_f32_e32 v160, v160
	v_exp_f32_e32 v161, v161
	v_exp_f32_e32 v162, v162
	v_exp_f32_e32 v163, v163
	v_exp_f32_e32 v164, v164
	v_exp_f32_e32 v165, v165
	v_pk_add_f32 v[158:159], v[158:159], 1.0 op_sel_hi:[1,0]
	v_pk_add_f32 v[160:161], v[160:161], 1.0 op_sel_hi:[1,0]
	v_rcp_f32_e32 v158, v158
	v_rcp_f32_e32 v159, v159
	v_pk_add_f32 v[162:163], v[162:163], 1.0 op_sel_hi:[1,0]
	v_pk_add_f32 v[164:165], v[164:165], 1.0 op_sel_hi:[1,0]
	v_rcp_f32_e32 v160, v160
	v_rcp_f32_e32 v161, v161
	v_rcp_f32_e32 v162, v162
	v_rcp_f32_e32 v163, v163
	v_rcp_f32_e32 v164, v164
	v_rcp_f32_e32 v165, v165
	v_mad_i64_i32 v[156:157], s[18:19], s20, v155, 0
	v_pk_mul_f32 v[158:159], v[118:119], v[158:159]
	v_lshl_add_u64 v[156:157], v[156:157], 1, s[8:9]
	v_pk_mul_f32 v[158:159], v[98:99], v[158:159]
	v_pk_mul_f32 v[160:161], v[120:121], v[160:161]
	v_pk_mul_f32 v[162:163], v[110:111], v[162:163]
	v_pk_mul_f32 v[164:165], v[112:113], v[164:165]
	v_pk_mul_f32 v[160:161], v[100:101], v[160:161]
	v_pk_mul_f32 v[162:163], v[90:91], v[162:163]
	v_pk_mul_f32 v[164:165], v[92:93], v[164:165]
	v_lshl_add_u64 v[166:167], v[156:157], 0, v[142:143]
	v_cvt_pk_bf16_f32 v156, v158, v159
	v_cvt_pk_bf16_f32 v157, v160, v161
	v_cvt_pk_bf16_f32 v158, v162, v163
	v_cvt_pk_bf16_f32 v159, v164, v165
	s_waitcnt lgkmcnt(0)
	global_store_dwordx4 v[246:247], v[248:251], off
	ds_write_b128 v244, v[156:159]
	v_lshl_add_u64 v[246:247], v[166:167], 0, v[252:253]
	ds_read_b128 v[248:251], v245
	v_pk_mul_f32 v[160:161], v[104:105], s[92:93] op_sel_hi:[1,0]
	v_pk_mul_f32 v[162:163], v[94:95], s[92:93] op_sel_hi:[1,0]
	v_pk_mul_f32 v[158:159], v[102:103], s[92:93] op_sel_hi:[1,0]
	v_pk_mul_f32 v[164:165], v[96:97], s[92:93] op_sel_hi:[1,0]
	v_exp_f32_e32 v158, v158
	v_exp_f32_e32 v159, v159
	v_exp_f32_e32 v160, v160
	v_exp_f32_e32 v161, v161
	v_exp_f32_e32 v162, v162
	v_exp_f32_e32 v163, v163
	v_exp_f32_e32 v164, v164
	v_exp_f32_e32 v165, v165
	v_pk_add_f32 v[158:159], v[158:159], 1.0 op_sel_hi:[1,0]
	v_pk_add_f32 v[160:161], v[160:161], 1.0 op_sel_hi:[1,0]
	v_rcp_f32_e32 v158, v158
	v_rcp_f32_e32 v159, v159
	v_pk_add_f32 v[162:163], v[162:163], 1.0 op_sel_hi:[1,0]
	v_pk_add_f32 v[164:165], v[164:165], 1.0 op_sel_hi:[1,0]
	v_rcp_f32_e32 v160, v160
	v_rcp_f32_e32 v161, v161
	v_rcp_f32_e32 v162, v162
	v_rcp_f32_e32 v163, v163
	v_rcp_f32_e32 v164, v164
	v_rcp_f32_e32 v165, v165
	v_mad_i64_i32 v[156:157], s[18:19], s20, v154, 0
	v_pk_mul_f32 v[158:159], v[102:103], v[158:159]
	v_lshl_add_u64 v[156:157], v[156:157], 1, s[8:9]
	v_pk_mul_f32 v[158:159], v[82:83], v[158:159]
	v_pk_mul_f32 v[160:161], v[104:105], v[160:161]
	v_pk_mul_f32 v[162:163], v[94:95], v[162:163]
	v_pk_mul_f32 v[164:165], v[96:97], v[164:165]
	v_pk_mul_f32 v[160:161], v[84:85], v[160:161]
	v_pk_mul_f32 v[162:163], v[74:75], v[162:163]
	v_pk_mul_f32 v[164:165], v[76:77], v[164:165]
	v_lshl_add_u64 v[166:167], v[156:157], 0, v[142:143]
	v_cvt_pk_bf16_f32 v156, v158, v159
	v_cvt_pk_bf16_f32 v157, v160, v161
	v_cvt_pk_bf16_f32 v158, v162, v163
	v_cvt_pk_bf16_f32 v159, v164, v165
	s_waitcnt lgkmcnt(0)
; __device__ __forceinline__ unsigned cvt_pk_bf16(float lo, float hi) { unsigned r; asm volatile("v_cvt_pk_bf16_f32 %0, %1, %2" : "=v"(r) : "v"(lo), "v"(hi)); return r; }
;     __device__ __forceinline__ void operator()(const f32x4 (&acc)[2][2][4][2], const Unit& u, int wr, int wc, int fr, int fq) const {
;     ...
;         const int col0 = u.pn * HALF + wc * 32 + 8 * fq;
; #pragma unroll
;         for (int ai = 0; ai < 2; ++ai)
; #pragma unroll
;             for (int m = 0; m < 4; ++m) { bf16_t* rowp = O + (size_t)(row0 + ai * HALF + m * 16) * ldc + col0;
;                 f32x2 h[4];
; #pragma unroll
;                 for (int n = 0; n < 2; ++n)
; #pragma unroll
;                     for (int j = 0; j < 2; ++j) { const f32x2 g = {acc[ai][0][m][n][2 * j], acc[ai][0][m][n][2 * j + 1]}, up = {acc[ai][1][m][n][2 * j], acc[ai][1][m][n][2 * j + 1]};
;                         const f32x2 t = g * (-1.44269504089f); f32x2 e; e.x = __builtin_amdgcn_exp2f(t.x); e.y = __builtin_amdgcn_exp2f(t.y);
;                         const f32x2 d = e + 1.0f; f32x2 r; r.x = __builtin_amdgcn_rcpf(d.x); r.y = __builtin_amdgcn_rcpf(d.y);
;                         h[n * 2 + j] = (g * r) * up; }
;                 u32x4 w; w.x = cvt_pk_bf16(h[0].x, h[0].y); w.y = cvt_pk_bf16(h[1].x, h[1].y); w.z = cvt_pk_bf16(h[2].x, h[2].y); w.w = cvt_pk_bf16(h[3].x, h[3].y);
;                 *(u32x4*)rowp = w; }
	global_store_dwordx4 v[246:247], v[248:251], off
	ds_write_b128 v244, v[156:159]
	v_lshl_add_u64 v[246:247], v[166:167], 0, v[252:253]
	ds_read_b128 v[248:251], v245
	v_pk_mul_f32 v[160:161], v[88:89], s[92:93] op_sel_hi:[1,0]
	v_pk_mul_f32 v[162:163], v[78:79], s[92:93] op_sel_hi:[1,0]
	v_pk_mul_f32 v[158:159], v[86:87], s[92:93] op_sel_hi:[1,0]
	v_pk_mul_f32 v[164:165], v[80:81], s[92:93] op_sel_hi:[1,0]
	v_exp_f32_e32 v158, v158
	v_exp_f32_e32 v159, v159
	v_exp_f32_e32 v160, v160
	v_exp_f32_e32 v161, v161
	v_exp_f32_e32 v162, v162
	v_exp_f32_e32 v163, v163
	v_exp_f32_e32 v164, v164
	v_exp_f32_e32 v165, v165
	v_pk_add_f32 v[158:159], v[158:159], 1.0 op_sel_hi:[1,0]
	v_pk_add_f32 v[160:161], v[160:161], 1.0 op_sel_hi:[1,0]
	v_rcp_f32_e32 v158, v158
	v_rcp_f32_e32 v159, v159
	v_pk_add_f32 v[162:163], v[162:163], 1.0 op_sel_hi:[1,0]
	v_pk_add_f32 v[164:165], v[164:165], 1.0 op_sel_hi:[1,0]
	v_rcp_f32_e32 v160, v160
	v_rcp_f32_e32 v161, v161
	v_rcp_f32_e32 v162, v162
	v_rcp_f32_e32 v163, v163
	v_rcp_f32_e32 v164, v164
	v_rcp_f32_e32 v165, v165
	v_mad_i64_i32 v[156:157], s[18:19], s20, v153, 0
	v_pk_mul_f32 v[158:159], v[86:87], v[158:159]
	v_lshl_add_u64 v[156:157], v[156:157], 1, s[8:9]
	v_pk_mul_f32 v[158:159], v[70:71], v[158:159]
	v_pk_mul_f32 v[160:161], v[88:89], v[160:161]
	v_pk_mul_f32 v[162:163], v[78:79], v[162:163]
	v_pk_mul_f32 v[164:165], v[80:81], v[164:165]
	v_pk_mul_f32 v[160:161], v[72:73], v[160:161]
	v_pk_mul_f32 v[162:163], v[66:67], v[162:163]
	v_pk_mul_f32 v[164:165], v[68:69], v[164:165]
	v_lshl_add_u64 v[166:167], v[156:157], 0, v[142:143]
	v_cvt_pk_bf16_f32 v156, v158, v159
	v_cvt_pk_bf16_f32 v157, v160, v161
	v_cvt_pk_bf16_f32 v158, v162, v163
	v_cvt_pk_bf16_f32 v159, v164, v165
	s_waitcnt lgkmcnt(0)
	global_store_dwordx4 v[246:247], v[248:251], off
	ds_write_b128 v244, v[156:159]
	v_lshl_add_u64 v[246:247], v[166:167], 0, v[252:253]
	ds_read_b128 v[248:251], v245
	v_pk_mul_f32 v[160:161], v[64:65], s[92:93] op_sel_hi:[1,0]
	v_pk_mul_f32 v[162:163], v[58:59], s[92:93] op_sel_hi:[1,0]
	v_pk_mul_f32 v[158:159], v[62:63], s[92:93] op_sel_hi:[1,0]
	v_pk_mul_f32 v[164:165], v[60:61], s[92:93] op_sel_hi:[1,0]
	v_exp_f32_e32 v158, v158
	v_exp_f32_e32 v159, v159
	v_exp_f32_e32 v160, v160
	v_exp_f32_e32 v161, v161
	v_exp_f32_e32 v162, v162
	v_exp_f32_e32 v163, v163
	v_exp_f32_e32 v164, v164
	v_exp_f32_e32 v165, v165
	v_pk_add_f32 v[158:159], v[158:159], 1.0 op_sel_hi:[1,0]
	v_pk_add_f32 v[160:161], v[160:161], 1.0 op_sel_hi:[1,0]
	v_rcp_f32_e32 v158, v158
	v_rcp_f32_e32 v159, v159
	v_pk_add_f32 v[162:163], v[162:163], 1.0 op_sel_hi:[1,0]
	v_pk_add_f32 v[164:165], v[164:165], 1.0 op_sel_hi:[1,0]
	v_rcp_f32_e32 v160, v160
	v_rcp_f32_e32 v161, v161
	v_rcp_f32_e32 v162, v162
	v_rcp_f32_e32 v163, v163
	v_rcp_f32_e32 v164, v164
	v_rcp_f32_e32 v165, v165
	v_mad_i64_i32 v[156:157], s[18:19], s20, v152, 0
	v_pk_mul_f32 v[158:159], v[62:63], v[158:159]
	v_lshl_add_u64 v[156:157], v[156:157], 1, s[8:9]
	v_pk_mul_f32 v[158:159], v[50:51], v[158:159]
	v_pk_mul_f32 v[160:161], v[64:65], v[160:161]
	v_pk_mul_f32 v[162:163], v[58:59], v[162:163]
	v_pk_mul_f32 v[164:165], v[60:61], v[164:165]
	v_pk_mul_f32 v[160:161], v[52:53], v[160:161]
	v_pk_mul_f32 v[162:163], v[42:43], v[162:163]
	v_pk_mul_f32 v[164:165], v[44:45], v[164:165]
	v_lshl_add_u64 v[166:167], v[156:157], 0, v[142:143]
	v_cvt_pk_bf16_f32 v156, v158, v159
	v_cvt_pk_bf16_f32 v157, v160, v161
	v_cvt_pk_bf16_f32 v158, v162, v163
	v_cvt_pk_bf16_f32 v159, v164, v165
	s_waitcnt lgkmcnt(0)
	global_store_dwordx4 v[246:247], v[248:251], off
	ds_write_b128 v244, v[156:159]
	v_lshl_add_u64 v[246:247], v[166:167], 0, v[252:253]
	ds_read_b128 v[248:251], v245
	v_pk_mul_f32 v[160:161], v[56:57], s[92:93] op_sel_hi:[1,0]
	v_pk_mul_f32 v[162:163], v[46:47], s[92:93] op_sel_hi:[1,0]
	v_pk_mul_f32 v[158:159], v[54:55], s[92:93] op_sel_hi:[1,0]
	v_pk_mul_f32 v[164:165], v[48:49], s[92:93] op_sel_hi:[1,0]
	v_exp_f32_e32 v158, v158
	v_exp_f32_e32 v159, v159
	v_exp_f32_e32 v160, v160
	v_exp_f32_e32 v161, v161
	v_exp_f32_e32 v162, v162
	v_exp_f32_e32 v163, v163
	v_exp_f32_e32 v164, v164
	v_exp_f32_e32 v165, v165
	v_pk_add_f32 v[158:159], v[158:159], 1.0 op_sel_hi:[1,0]
	v_pk_add_f32 v[160:161], v[160:161], 1.0 op_sel_hi:[1,0]
	v_rcp_f32_e32 v158, v158
	v_rcp_f32_e32 v159, v159
	v_pk_add_f32 v[162:163], v[162:163], 1.0 op_sel_hi:[1,0]
	v_pk_add_f32 v[164:165], v[164:165], 1.0 op_sel_hi:[1,0]
	v_rcp_f32_e32 v160, v160
	v_rcp_f32_e32 v161, v161
	v_rcp_f32_e32 v162, v162
	v_rcp_f32_e32 v163, v163
	v_rcp_f32_e32 v164, v164
	v_rcp_f32_e32 v165, v165
	v_mad_i64_i32 v[156:157], s[18:19], s20, v151, 0
	v_pk_mul_f32 v[158:159], v[54:55], v[158:159]
	v_lshl_add_u64 v[156:157], v[156:157], 1, s[8:9]
	v_pk_mul_f32 v[158:159], v[34:35], v[158:159]
	v_pk_mul_f32 v[160:161], v[56:57], v[160:161]
	v_pk_mul_f32 v[162:163], v[46:47], v[162:163]
	v_pk_mul_f32 v[164:165], v[48:49], v[164:165]
	v_pk_mul_f32 v[160:161], v[36:37], v[160:161]
	v_pk_mul_f32 v[162:163], v[26:27], v[162:163]
	v_pk_mul_f32 v[164:165], v[28:29], v[164:165]
	v_lshl_add_u64 v[166:167], v[156:157], 0, v[142:143]
	v_cvt_pk_bf16_f32 v156, v158, v159
	v_cvt_pk_bf16_f32 v157, v160, v161
	v_cvt_pk_bf16_f32 v158, v162, v163
	v_cvt_pk_bf16_f32 v159, v164, v165
	s_waitcnt lgkmcnt(0)
; __device__ __forceinline__ unsigned cvt_pk_bf16(float lo, float hi) { unsigned r; asm volatile("v_cvt_pk_bf16_f32 %0, %1, %2" : "=v"(r) : "v"(lo), "v"(hi)); return r; }
;     __device__ __forceinline__ void operator()(const f32x4 (&acc)[2][2][4][2], const Unit& u, int wr, int wc, int fr, int fq) const {
;     ...
;             for (int m = 0; m < 4; ++m) { bf16_t* rowp = O + (size_t)(row0 + ai * HALF + m * 16) * ldc + col0;
;                 f32x2 h[4];
; #pragma unroll
;                 for (int n = 0; n < 2; ++n)
; #pragma unroll
;                     for (int j = 0; j < 2; ++j) { const f32x2 g = {acc[ai][0][m][n][2 * j], acc[ai][0][m][n][2 * j + 1]}, up = {acc[ai][1][m][n][2 * j], acc[ai][1][m][n][2 * j + 1]};
;                         const f32x2 t = g * (-1.44269504089f); f32x2 e; e.x = __builtin_amdgcn_exp2f(t.x); e.y = __builtin_amdgcn_exp2f(t.y);
;                         const f32x2 d = e + 1.0f; f32x2 r; r.x = __builtin_amdgcn_rcpf(d.x); r.y = __builtin_amdgcn_rcpf(d.y);
;                         h[n * 2 + j] = (g * r) * up; }
;                 u32x4 w; w.x = cvt_pk_bf16(h[0].x, h[0].y); w.y = cvt_pk_bf16(h[1].x, h[1].y); w.z = cvt_pk_bf16(h[2].x, h[2].y); w.w = cvt_pk_bf16(h[3].x, h[3].y);
;                 *(u32x4*)rowp = w; }
	global_store_dwordx4 v[246:247], v[248:251], off
	ds_write_b128 v244, v[156:159]
	v_lshl_add_u64 v[246:247], v[166:167], 0, v[252:253]
	ds_read_b128 v[248:251], v245
	v_pk_mul_f32 v[160:161], v[40:41], s[92:93] op_sel_hi:[1,0]
	v_pk_mul_f32 v[162:163], v[30:31], s[92:93] op_sel_hi:[1,0]
	v_pk_mul_f32 v[158:159], v[38:39], s[92:93] op_sel_hi:[1,0]
	v_pk_mul_f32 v[164:165], v[32:33], s[92:93] op_sel_hi:[1,0]
	v_exp_f32_e32 v158, v158
	v_exp_f32_e32 v159, v159
	v_exp_f32_e32 v160, v160
	v_exp_f32_e32 v161, v161
	v_exp_f32_e32 v162, v162
	v_exp_f32_e32 v163, v163
	v_exp_f32_e32 v164, v164
	v_exp_f32_e32 v165, v165
	v_pk_add_f32 v[158:159], v[158:159], 1.0 op_sel_hi:[1,0]
	v_pk_add_f32 v[160:161], v[160:161], 1.0 op_sel_hi:[1,0]
	v_rcp_f32_e32 v158, v158
	v_rcp_f32_e32 v159, v159
	v_pk_add_f32 v[162:163], v[162:163], 1.0 op_sel_hi:[1,0]
	v_pk_add_f32 v[164:165], v[164:165], 1.0 op_sel_hi:[1,0]
	v_rcp_f32_e32 v160, v160
	v_rcp_f32_e32 v161, v161
	v_rcp_f32_e32 v162, v162
	v_rcp_f32_e32 v163, v163
	v_rcp_f32_e32 v164, v164
	v_rcp_f32_e32 v165, v165
	v_mad_i64_i32 v[156:157], s[18:19], s20, v150, 0
	v_pk_mul_f32 v[158:159], v[38:39], v[158:159]
	v_lshl_add_u64 v[156:157], v[156:157], 1, s[8:9]
	v_pk_mul_f32 v[158:159], v[18:19], v[158:159]
	v_pk_mul_f32 v[160:161], v[40:41], v[160:161]
	v_pk_mul_f32 v[162:163], v[30:31], v[162:163]
	v_pk_mul_f32 v[164:165], v[32:33], v[164:165]
	v_pk_mul_f32 v[160:161], v[20:21], v[160:161]
	v_pk_mul_f32 v[162:163], v[10:11], v[162:163]
	v_pk_mul_f32 v[164:165], v[12:13], v[164:165]
	v_lshl_add_u64 v[166:167], v[156:157], 0, v[142:143]
	v_cvt_pk_bf16_f32 v156, v158, v159
	v_cvt_pk_bf16_f32 v157, v160, v161
	v_cvt_pk_bf16_f32 v158, v162, v163
	v_cvt_pk_bf16_f32 v159, v164, v165
	s_waitcnt lgkmcnt(0)
	global_store_dwordx4 v[246:247], v[248:251], off
	ds_write_b128 v244, v[156:159]
	v_lshl_add_u64 v[246:247], v[166:167], 0, v[252:253]
	ds_read_b128 v[248:251], v245
	v_pk_mul_f32 v[160:161], v[24:25], s[92:93] op_sel_hi:[1,0]
	v_pk_mul_f32 v[162:163], v[14:15], s[92:93] op_sel_hi:[1,0]
	v_pk_mul_f32 v[158:159], v[22:23], s[92:93] op_sel_hi:[1,0]
	v_pk_mul_f32 v[164:165], v[16:17], s[92:93] op_sel_hi:[1,0]
	v_exp_f32_e32 v158, v158
	v_exp_f32_e32 v159, v159
	v_exp_f32_e32 v160, v160
	v_exp_f32_e32 v161, v161
	v_exp_f32_e32 v162, v162
	v_exp_f32_e32 v163, v163
	v_exp_f32_e32 v164, v164
	v_exp_f32_e32 v165, v165
	v_pk_add_f32 v[158:159], v[158:159], 1.0 op_sel_hi:[1,0]
	v_pk_add_f32 v[160:161], v[160:161], 1.0 op_sel_hi:[1,0]
	v_rcp_f32_e32 v158, v158
	v_rcp_f32_e32 v159, v159
	v_pk_add_f32 v[162:163], v[162:163], 1.0 op_sel_hi:[1,0]
	v_pk_add_f32 v[164:165], v[164:165], 1.0 op_sel_hi:[1,0]
	v_rcp_f32_e32 v160, v160
	v_rcp_f32_e32 v161, v161
	v_rcp_f32_e32 v162, v162
	v_rcp_f32_e32 v163, v163
	v_rcp_f32_e32 v164, v164
	v_rcp_f32_e32 v165, v165
	v_mad_i64_i32 v[156:157], s[18:19], s20, v149, 0
	v_lshl_add_u64 v[156:157], v[156:157], 1, s[8:9]
	v_pk_mul_f32 v[158:159], v[22:23], v[158:159]
	v_pk_mul_f32 v[160:161], v[24:25], v[160:161]
	v_pk_mul_f32 v[158:159], v[6:7], v[158:159]
	v_pk_mul_f32 v[162:163], v[14:15], v[162:163]
	v_pk_mul_f32 v[164:165], v[16:17], v[164:165]
	v_lshl_add_u64 v[142:143], v[156:157], 0, v[142:143]
	v_pk_mul_f32 v[160:161], v[8:9], v[160:161]
	v_pk_mul_f32 v[162:163], v[2:3], v[162:163]
	v_pk_mul_f32 v[164:165], v[4:5], v[164:165]
	v_cvt_pk_bf16_f32 v156, v158, v159
	v_cvt_pk_bf16_f32 v157, v160, v161
	v_cvt_pk_bf16_f32 v158, v162, v163
	s_mov_b64 s[38:39], 0
	v_cvt_pk_bf16_f32 v159, v164, v165
	s_waitcnt lgkmcnt(0)
	global_store_dwordx4 v[246:247], v[248:251], off
	ds_write_b128 v244, v[156:159]
	v_lshl_add_u64 v[246:247], v[142:143], 0, v[252:253]
	ds_read_b128 v[248:251], v245
	s_waitcnt lgkmcnt(0)
	global_store_dwordx4 v[246:247], v[248:251], off
